# removed the 16 s_setprio 1/0 toggles around the MFMA groups in the GEMM K-loop
# baseline (speedup 1.0000x reference)
; #define PG8_STAGE(bufoff, gbase, voff) do { _Pragma("unroll") for (int _i = 0; _i < 2; ++_i) \
;         __builtin_amdgcn_global_load_lds((const unsigned*)((const char*)(gbase) + (voff)[_i]), (LAS unsigned*)(lds + (bufoff) + ldsw + _i * 8192), 16, 0, 0); } while (0)
; #define PG8_LDA(dst, b, h) do { _Pragma("unroll") for (int m = 0; m < 4; ++m) _Pragma("unroll") for (int k = 0; k < 2; ++k) dst[m][k] = *(const LAS bf16x8*)(lds + PG8_SA(b, h) + aoff + m * 2048 + k * 1024); } while (0)
; #define PG8_LDB(dst, b, h) do { _Pragma("unroll") for (int n = 0; n < 2; ++n) _Pragma("unroll") for (int k = 0; k < 2; ++k) dst[n][k] = *(const LAS bf16x8*)(lds + PG8_SB(b, h) + boff + n * 2048 + k * 1024); } while (0)
; #define PG8_MMA(ai, bj, At, Bt) do { __builtin_amdgcn_s_setprio(1); _Pragma("unroll") for (int m = 0; m < 4; ++m) _Pragma("unroll") for (int n = 0; n < 2; ++n) _Pragma("unroll") for (int k = 0; k < 2; ++k) \
;         acc[ai][bj][m][n] = __builtin_amdgcn_mfma_f32_16x16x32_bf16(Bt[n][k], At[m][k], acc[ai][bj][m][n], 0, 0, 0); __builtin_amdgcn_s_setprio(0); } while (0)
; #define PG8_WAIT_L(n) asm volatile("s_waitcnt lgkmcnt(" #n ")" ::: "memory")
; #define PG8_BAR __builtin_amdgcn_s_barrier()
; #define PG8_SCHED __builtin_amdgcn_sched_barrier(0)
; __device__ __forceinline__ void gemm_phase(LAS unsigned char* lds, CParams& p, const Job& jb) {
;     ...
;             PG8_LDB(B0, 0, 0); PG8_SCHED; PG8_LDA(At, 0, 0); PG8_STAGE(PG8_SA(1, 1), a1 + hstepA, voffA);
;             PG8_WAIT_L(8); PG8_BAR; PG8_WAIT_L(0); PG8_MMA(0, 0, At, B0); PG8_BAR; PG8_SCHED;
;             PG8_LDB(B1, 0, 1); PG8_STAGE(PG8_SB(0, 0), b2, voffB);
;             PG8_BAR; PG8_WAIT_L(0); PG8_MMA(0, 1, At, B1); PG8_BAR;
;             PG8_LDA(At, 0, 1); PG8_STAGE(PG8_SA(0, 0), a2, voffA);
;             PG8_BAR; PG8_WAIT_L(0); PG8_MMA(1, 0, At, B0); PG8_BAR; PG8_SCHED;
.LBB0_631:
	s_add_i32 s1, s1, 2
	s_add_u32 s12, s24, s10
	s_addc_u32 s13, s25, s11
	s_add_u32 s12, s12, 0x100
	s_addc_u32 s13, s13, 0
	s_add_u32 s14, s97, s10
	s_addc_u32 s15, s2, s11
	s_add_i32 s16, 0, 0x10000
	v_add_u32_e32 v144, s16, v213
	ds_read_b128 v[132:135], v144
	ds_read_b128 v[136:139], v144 offset:1024
	ds_read_b128 v[140:143], v144 offset:2048
	ds_read_b128 v[144:147], v144 offset:3072
	s_cmp_eq_u32 s85, s10
	s_cselect_b32 s13, s5, s13
	s_cselect_b32 s12, s4, s12
	s_cselect_b32 s15, s87, s15
	s_cselect_b32 s14, s86, s14
	v_lshl_add_u64 v[216:217], v[128:129], 0, s[10:11]
	s_add_i32 m0, s65, 0xc000
	ds_read_b128 v[148:151], v214
	ds_read_b128 v[152:155], v214 offset:1024
	ds_read_b128 v[156:159], v214 offset:2048
	ds_read_b128 v[172:175], v214 offset:3072
	ds_read_b128 v[176:179], v214 offset:4096
	ds_read_b128 v[180:183], v214 offset:5120
	ds_read_b128 v[184:187], v214 offset:6144
	ds_read_b128 v[188:191], v214 offset:7168
	global_load_lds_dwordx4 v[216:217], off
	v_lshl_add_u64 v[216:217], v[130:131], 0, s[10:11]
	s_add_i32 m0, s65, 0xe000
	s_nop 0
	global_load_lds_dwordx4 v[216:217], off
	s_waitcnt lgkmcnt(8)
	s_barrier
	s_waitcnt lgkmcnt(0)
	s_waitcnt lgkmcnt(0)
	v_mfma_f32_16x16x32_bf16 v[124:127], v[132:135], v[148:151], v[124:127]
	v_mfma_f32_16x16x32_bf16 v[120:123], v[140:143], v[148:151], v[120:123]
	v_mfma_f32_16x16x32_bf16 v[116:119], v[132:135], v[156:159], v[116:119]
	v_mfma_f32_16x16x32_bf16 v[112:115], v[140:143], v[156:159], v[112:115]
	v_mfma_f32_16x16x32_bf16 v[108:111], v[132:135], v[176:179], v[108:111]
	v_mfma_f32_16x16x32_bf16 v[104:107], v[140:143], v[176:179], v[104:107]
	v_mfma_f32_16x16x32_bf16 v[100:103], v[132:135], v[184:187], v[100:103]
	v_mfma_f32_16x16x32_bf16 v[96:99], v[140:143], v[184:187], v[96:99]
	v_mfma_f32_16x16x32_bf16 v[124:127], v[136:139], v[152:155], v[124:127]
	v_mfma_f32_16x16x32_bf16 v[120:123], v[144:147], v[152:155], v[120:123]
	v_mfma_f32_16x16x32_bf16 v[116:119], v[136:139], v[172:175], v[116:119]
	v_mfma_f32_16x16x32_bf16 v[112:115], v[144:147], v[172:175], v[112:115]
	v_mfma_f32_16x16x32_bf16 v[108:111], v[136:139], v[180:183], v[108:111]
	v_mfma_f32_16x16x32_bf16 v[104:107], v[144:147], v[180:183], v[104:107]
	v_mfma_f32_16x16x32_bf16 v[100:103], v[136:139], v[188:191], v[100:103]
	v_mfma_f32_16x16x32_bf16 v[96:99], v[144:147], v[188:191], v[96:99]
	s_barrier
	s_add_i32 s17, 0, 0x14000
	s_add_i32 s16, s16, s64
	v_add_u32_e32 v215, s17, v213
	v_lshl_add_u64 v[232:233], s[14:15], 0, v[160:161]
	s_mov_b32 m0, s16
	ds_read_b128 v[216:219], v215
	ds_read_b128 v[220:223], v215 offset:1024
	ds_read_b128 v[224:227], v215 offset:2048
	ds_read_b128 v[228:231], v215 offset:3072
	global_load_lds_dwordx4 v[232:233], off
	v_lshl_add_u64 v[234:235], s[14:15], 0, v[166:167]
	s_add_i32 m0, s16, 0x2000
	s_nop 0
	global_load_lds_dwordx4 v[234:235], off
	s_barrier
	s_waitcnt lgkmcnt(0)
	s_waitcnt lgkmcnt(0)
	v_mfma_f32_16x16x32_bf16 v[92:95], v[216:219], v[148:151], v[92:95]
	v_mfma_f32_16x16x32_bf16 v[88:91], v[224:227], v[148:151], v[88:91]
	v_mfma_f32_16x16x32_bf16 v[84:87], v[216:219], v[156:159], v[84:87]
	v_mfma_f32_16x16x32_bf16 v[80:83], v[224:227], v[156:159], v[80:83]
	v_mfma_f32_16x16x32_bf16 v[76:79], v[216:219], v[176:179], v[76:79]
	v_mfma_f32_16x16x32_bf16 v[72:75], v[224:227], v[176:179], v[72:75]
	v_mfma_f32_16x16x32_bf16 v[68:71], v[216:219], v[184:187], v[68:71]
	v_mfma_f32_16x16x32_bf16 v[64:67], v[224:227], v[184:187], v[64:67]
	v_mfma_f32_16x16x32_bf16 v[92:95], v[220:223], v[152:155], v[92:95]
	v_mfma_f32_16x16x32_bf16 v[88:91], v[228:231], v[152:155], v[88:91]
	v_mfma_f32_16x16x32_bf16 v[84:87], v[220:223], v[172:175], v[84:87]
	v_mfma_f32_16x16x32_bf16 v[80:83], v[228:231], v[172:175], v[80:83]
	v_mfma_f32_16x16x32_bf16 v[76:79], v[220:223], v[180:183], v[76:79]
	v_mfma_f32_16x16x32_bf16 v[72:75], v[228:231], v[180:183], v[72:75]
	v_mfma_f32_16x16x32_bf16 v[68:71], v[220:223], v[188:191], v[68:71]
	v_mfma_f32_16x16x32_bf16 v[64:67], v[228:231], v[188:191], v[64:67]
	s_mov_b32 m0, s65
	v_lshl_add_u64 v[236:237], s[12:13], 0, v[162:163]
	s_barrier
	ds_read_b128 v[148:151], v214 offset:16384
	ds_read_b128 v[152:155], v214 offset:17408
	ds_read_b128 v[156:159], v214 offset:18432
	ds_read_b128 v[172:175], v214 offset:19456
	ds_read_b128 v[176:179], v214 offset:20480
	ds_read_b128 v[180:183], v214 offset:21504
	ds_read_b128 v[184:187], v214 offset:22528
	ds_read_b128 v[188:191], v214 offset:23552
	global_load_lds_dwordx4 v[236:237], off
	v_lshl_add_u64 v[238:239], s[12:13], 0, v[164:165]
	s_mov_b32 m0, s66
	s_nop 0
	global_load_lds_dwordx4 v[238:239], off
	s_barrier
	s_waitcnt lgkmcnt(0)
	s_waitcnt lgkmcnt(0)
	v_mfma_f32_16x16x32_bf16 v[60:63], v[132:135], v[148:151], v[60:63]
	v_mfma_f32_16x16x32_bf16 v[56:59], v[140:143], v[148:151], v[56:59]
	v_mfma_f32_16x16x32_bf16 v[52:55], v[132:135], v[156:159], v[52:55]
	v_mfma_f32_16x16x32_bf16 v[48:51], v[140:143], v[156:159], v[48:51]
	v_mfma_f32_16x16x32_bf16 v[44:47], v[132:135], v[176:179], v[44:47]
	v_mfma_f32_16x16x32_bf16 v[40:43], v[140:143], v[176:179], v[40:43]
	v_mfma_f32_16x16x32_bf16 v[36:39], v[132:135], v[184:187], v[36:39]
	v_mfma_f32_16x16x32_bf16 v[32:35], v[140:143], v[184:187], v[32:35]
	v_mfma_f32_16x16x32_bf16 v[60:63], v[136:139], v[152:155], v[60:63]
	v_mfma_f32_16x16x32_bf16 v[56:59], v[144:147], v[152:155], v[56:59]
	v_mfma_f32_16x16x32_bf16 v[52:55], v[136:139], v[172:175], v[52:55]
	v_mfma_f32_16x16x32_bf16 v[48:51], v[144:147], v[172:175], v[48:51]
	v_mfma_f32_16x16x32_bf16 v[44:47], v[136:139], v[180:183], v[44:47]
	v_mfma_f32_16x16x32_bf16 v[40:43], v[144:147], v[180:183], v[40:43]
	v_mfma_f32_16x16x32_bf16 v[36:39], v[136:139], v[188:191], v[36:39]
	v_mfma_f32_16x16x32_bf16 v[32:35], v[144:147], v[188:191], v[32:35]
	s_barrier
; #define PG8_STAGE(bufoff, gbase, voff) do { _Pragma("unroll") for (int _i = 0; _i < 2; ++_i) \
;         __builtin_amdgcn_global_load_lds((const unsigned*)((const char*)(gbase) + (voff)[_i]), (LAS unsigned*)(lds + (bufoff) + ldsw + _i * 8192), 16, 0, 0); } while (0)
; #define PG8_LDA(dst, b, h) do { _Pragma("unroll") for (int m = 0; m < 4; ++m) _Pragma("unroll") for (int k = 0; k < 2; ++k) dst[m][k] = *(const LAS bf16x8*)(lds + PG8_SA(b, h) + aoff + m * 2048 + k * 1024); } while (0)
; #define PG8_LDB(dst, b, h) do { _Pragma("unroll") for (int n = 0; n < 2; ++n) _Pragma("unroll") for (int k = 0; k < 2; ++k) dst[n][k] = *(const LAS bf16x8*)(lds + PG8_SB(b, h) + boff + n * 2048 + k * 1024); } while (0)
; #define PG8_MMA(ai, bj, At, Bt) do { __builtin_amdgcn_s_setprio(1); _Pragma("unroll") for (int m = 0; m < 4; ++m) _Pragma("unroll") for (int n = 0; n < 2; ++n) _Pragma("unroll") for (int k = 0; k < 2; ++k) \
;         acc[ai][bj][m][n] = __builtin_amdgcn_mfma_f32_16x16x32_bf16(Bt[n][k], At[m][k], acc[ai][bj][m][n], 0, 0, 0); __builtin_amdgcn_s_setprio(0); } while (0)
; #define PG8_WAIT_V(n) asm volatile("s_waitcnt vmcnt(" #n ")" ::: "memory")
; #define PG8_WAIT_L(n) asm volatile("s_waitcnt lgkmcnt(" #n ")" ::: "memory")
; #define PG8_BAR __builtin_amdgcn_s_barrier()
; #define PG8_SCHED __builtin_amdgcn_sched_barrier(0)
; __device__ __forceinline__ void gemm_phase(LAS unsigned char* lds, CParams& p, const Job& jb) {
;     ...
;             PG8_STAGE(PG8_SB(0, 1), b2 + hstepB, voffB);
;             PG8_WAIT_V(6); PG8_BAR; PG8_MMA(1, 1, At, B1); PG8_BAR;
;             PG8_LDB(B0, 1, 0); PG8_SCHED; PG8_LDA(At, 1, 0); PG8_STAGE(PG8_SA(0, 1), a2 + hstepA, voffA);
;             PG8_WAIT_L(8); PG8_BAR; PG8_WAIT_L(0); PG8_MMA(0, 0, At, B0); PG8_BAR; PG8_SCHED;
;             PG8_LDB(B1, 1, 1); PG8_STAGE(PG8_SB(1, 0), b3, voffB);
;             PG8_BAR; PG8_WAIT_L(0); PG8_MMA(0, 1, At, B1); PG8_BAR;
;             PG8_LDA(At, 1, 1); PG8_STAGE(PG8_SA(1, 0), a3, voffA);
	s_add_u32 s14, s14, s76
	s_addc_u32 s15, s15, s77
	s_add_i32 s16, s17, s64
	v_lshl_add_u64 v[240:241], s[14:15], 0, v[160:161]
	s_mov_b32 m0, s16
	v_lshl_add_u64 v[242:243], s[14:15], 0, v[166:167]
	global_load_lds_dwordx4 v[240:241], off
	s_add_i32 m0, s16, 0x2000
	s_nop 0
	global_load_lds_dwordx4 v[242:243], off
	s_waitcnt vmcnt(6)
	s_barrier
	v_mfma_f32_16x16x32_bf16 v[28:31], v[216:219], v[148:151], v[28:31]
	v_mfma_f32_16x16x32_bf16 v[24:27], v[224:227], v[148:151], v[24:27]
	v_mfma_f32_16x16x32_bf16 v[20:23], v[216:219], v[156:159], v[20:23]
	v_mfma_f32_16x16x32_bf16 v[16:19], v[224:227], v[156:159], v[16:19]
	v_mfma_f32_16x16x32_bf16 v[12:15], v[216:219], v[176:179], v[12:15]
	v_mfma_f32_16x16x32_bf16 v[8:11], v[224:227], v[176:179], v[8:11]
	v_mfma_f32_16x16x32_bf16 v[4:7], v[216:219], v[184:187], v[4:7]
	v_mfma_f32_16x16x32_bf16 v[0:3], v[224:227], v[184:187], v[0:3]
	v_mfma_f32_16x16x32_bf16 v[28:31], v[220:223], v[152:155], v[28:31]
	v_mfma_f32_16x16x32_bf16 v[24:27], v[228:231], v[152:155], v[24:27]
	v_mfma_f32_16x16x32_bf16 v[20:23], v[220:223], v[172:175], v[20:23]
	v_mfma_f32_16x16x32_bf16 v[16:19], v[228:231], v[172:175], v[16:19]
	v_mfma_f32_16x16x32_bf16 v[12:15], v[220:223], v[180:183], v[12:15]
	v_mfma_f32_16x16x32_bf16 v[8:11], v[228:231], v[180:183], v[8:11]
	v_mfma_f32_16x16x32_bf16 v[4:7], v[220:223], v[188:191], v[4:7]
	v_mfma_f32_16x16x32_bf16 v[0:3], v[228:231], v[188:191], v[0:3]
	s_add_i32 s14, 0, 0x18000
	v_add_u32_e32 v144, s14, v213
	s_barrier
	ds_read_b128 v[132:135], v144
	ds_read_b128 v[136:139], v144 offset:1024
	ds_read_b128 v[140:143], v144 offset:2048
	ds_read_b128 v[144:147], v144 offset:3072
	s_add_u32 s12, s12, s74
	s_addc_u32 s13, s13, s75
	s_mov_b32 m0, s67
	v_lshl_add_u64 v[216:217], s[12:13], 0, v[162:163]
	ds_read_b128 v[148:151], v214 offset:32768
	ds_read_b128 v[152:155], v214 offset:33792
	ds_read_b128 v[156:159], v214 offset:34816
	ds_read_b128 v[172:175], v214 offset:35840
	ds_read_b128 v[176:179], v214 offset:36864
	ds_read_b128 v[180:183], v214 offset:37888
	ds_read_b128 v[184:187], v214 offset:38912
	ds_read_b128 v[188:191], v214 offset:39936
	global_load_lds_dwordx4 v[216:217], off
	v_lshl_add_u64 v[216:217], s[12:13], 0, v[164:165]
	s_mov_b32 m0, s94
	s_nop 0
	global_load_lds_dwordx4 v[216:217], off
	s_waitcnt lgkmcnt(8)
	s_barrier
	s_waitcnt lgkmcnt(0)
	s_waitcnt lgkmcnt(0)
	v_mfma_f32_16x16x32_bf16 v[124:127], v[132:135], v[148:151], v[124:127]
	v_mfma_f32_16x16x32_bf16 v[120:123], v[140:143], v[148:151], v[120:123]
	v_mfma_f32_16x16x32_bf16 v[116:119], v[132:135], v[156:159], v[116:119]
	v_mfma_f32_16x16x32_bf16 v[112:115], v[140:143], v[156:159], v[112:115]
	v_mfma_f32_16x16x32_bf16 v[108:111], v[132:135], v[176:179], v[108:111]
	v_mfma_f32_16x16x32_bf16 v[104:107], v[140:143], v[176:179], v[104:107]
	v_mfma_f32_16x16x32_bf16 v[100:103], v[132:135], v[184:187], v[100:103]
	v_mfma_f32_16x16x32_bf16 v[96:99], v[140:143], v[184:187], v[96:99]
	v_mfma_f32_16x16x32_bf16 v[124:127], v[136:139], v[152:155], v[124:127]
	v_mfma_f32_16x16x32_bf16 v[120:123], v[144:147], v[152:155], v[120:123]
	v_mfma_f32_16x16x32_bf16 v[116:119], v[136:139], v[172:175], v[116:119]
	v_mfma_f32_16x16x32_bf16 v[112:115], v[144:147], v[172:175], v[112:115]
	v_mfma_f32_16x16x32_bf16 v[108:111], v[136:139], v[180:183], v[108:111]
	v_mfma_f32_16x16x32_bf16 v[104:107], v[144:147], v[180:183], v[104:107]
	v_mfma_f32_16x16x32_bf16 v[100:103], v[136:139], v[188:191], v[100:103]
	v_mfma_f32_16x16x32_bf16 v[96:99], v[144:147], v[188:191], v[96:99]
	s_barrier
	s_add_i32 s12, 0, 0x1c000
	s_add_i32 s13, s14, s64
	v_add_u32_e32 v215, s12, v213
	v_lshl_add_u64 v[232:233], v[232:233], 0, s[90:91]
	s_mov_b32 m0, s13
	ds_read_b128 v[216:219], v215
	ds_read_b128 v[220:223], v215 offset:1024
	ds_read_b128 v[224:227], v215 offset:2048
	ds_read_b128 v[228:231], v215 offset:3072
	global_load_lds_dwordx4 v[232:233], off
	v_lshl_add_u64 v[232:233], v[234:235], 0, s[90:91]
	s_add_i32 m0, s13, 0x2000
	s_nop 0
	global_load_lds_dwordx4 v[232:233], off
	s_barrier
	s_waitcnt lgkmcnt(0)
	s_waitcnt lgkmcnt(0)
	v_mfma_f32_16x16x32_bf16 v[92:95], v[216:219], v[148:151], v[92:95]
	v_mfma_f32_16x16x32_bf16 v[88:91], v[224:227], v[148:151], v[88:91]
	v_mfma_f32_16x16x32_bf16 v[84:87], v[216:219], v[156:159], v[84:87]
	v_mfma_f32_16x16x32_bf16 v[80:83], v[224:227], v[156:159], v[80:83]
	v_mfma_f32_16x16x32_bf16 v[76:79], v[216:219], v[176:179], v[76:79]
	v_mfma_f32_16x16x32_bf16 v[72:75], v[224:227], v[176:179], v[72:75]
	v_mfma_f32_16x16x32_bf16 v[68:71], v[216:219], v[184:187], v[68:71]
	v_mfma_f32_16x16x32_bf16 v[64:67], v[224:227], v[184:187], v[64:67]
	v_mfma_f32_16x16x32_bf16 v[92:95], v[220:223], v[152:155], v[92:95]
	v_mfma_f32_16x16x32_bf16 v[88:91], v[228:231], v[152:155], v[88:91]
	v_mfma_f32_16x16x32_bf16 v[84:87], v[220:223], v[172:175], v[84:87]
	v_mfma_f32_16x16x32_bf16 v[80:83], v[228:231], v[172:175], v[80:83]
	v_mfma_f32_16x16x32_bf16 v[76:79], v[220:223], v[180:183], v[76:79]
	v_mfma_f32_16x16x32_bf16 v[72:75], v[228:231], v[180:183], v[72:75]
	v_mfma_f32_16x16x32_bf16 v[68:71], v[220:223], v[188:191], v[68:71]
	v_mfma_f32_16x16x32_bf16 v[64:67], v[228:231], v[188:191], v[64:67]
	s_mov_b32 m0, s33
	v_lshl_add_u64 v[232:233], v[236:237], 0, s[90:91]
	s_barrier
	ds_read_b128 v[148:151], v214 offset:49152
	ds_read_b128 v[152:155], v214 offset:50176
	ds_read_b128 v[156:159], v214 offset:51200
	ds_read_b128 v[172:175], v214 offset:52224
	ds_read_b128 v[176:179], v214 offset:53248
	ds_read_b128 v[180:183], v214 offset:54272
	ds_read_b128 v[184:187], v214 offset:55296
	ds_read_b128 v[188:191], v214 offset:56320
	global_load_lds_dwordx4 v[232:233], off
	v_lshl_add_u64 v[232:233], v[238:239], 0, s[90:91]
	s_mov_b32 m0, s60
	s_nop 0
	global_load_lds_dwordx4 v[232:233], off
	s_barrier
; #define FOR_ROWS _Pragma("unroll") for (int ai = 0; ai < 2; ++ai) _Pragma("unroll") for (int m = 0; m < 4; ++m)
; #define PG8_STAGE(bufoff, gbase, voff) do { _Pragma("unroll") for (int _i = 0; _i < 2; ++_i) \
;         __builtin_amdgcn_global_load_lds((const unsigned*)((const char*)(gbase) + (voff)[_i]), (LAS unsigned*)(lds + (bufoff) + ldsw + _i * 8192), 16, 0, 0); } while (0)
; #define PG8_MMA(ai, bj, At, Bt) do { __builtin_amdgcn_s_setprio(1); _Pragma("unroll") for (int m = 0; m < 4; ++m) _Pragma("unroll") for (int n = 0; n < 2; ++n) _Pragma("unroll") for (int k = 0; k < 2; ++k) \
;         acc[ai][bj][m][n] = __builtin_amdgcn_mfma_f32_16x16x32_bf16(Bt[n][k], At[m][k], acc[ai][bj][m][n], 0, 0, 0); __builtin_amdgcn_s_setprio(0); } while (0)
; #define PG8_WAIT_V(n) asm volatile("s_waitcnt vmcnt(" #n ")" ::: "memory")
; #define PG8_WAIT_L(n) asm volatile("s_waitcnt lgkmcnt(" #n ")" ::: "memory")
; #define PG8_BAR __builtin_amdgcn_s_barrier()
; #define PG8_SCHED __builtin_amdgcn_sched_barrier(0)
; __device__ __forceinline__ void epilogue(const int kind, CParams& p, const f32x4 (&acc)[2][2][4][2], const Unit& u, const int wr, const int wc, const int fr_in, const int fq_in) {
;     ...
;     case E_DOWN_HALF: {
;         FOR_ROWS { ROWDEF
; #pragma unroll
;             for (int bj = 0; bj < 2; ++bj) { float* hp = p.out + row * 1024 + u.pn * 256 + bj * 128 + cw;
; #pragma unroll
;                 for (int j = 0; j < 4; ++j) { unsafeAtomicAdd(hp + j, acc[ai][bj][m][0][j]); unsafeAtomicAdd(hp + 4 + j, acc[ai][bj][m][1][j]); } } }
;     } break;
; __device__ __forceinline__ void gemm_phase(LAS unsigned char* lds, CParams& p, const Job& jb) {
;     ...
;             PG8_BAR; PG8_WAIT_L(0); PG8_MMA(1, 0, At, B0); PG8_BAR; PG8_SCHED;
;             PG8_STAGE(PG8_SB(1, 1), b3 + hstepB, voffB);
;             PG8_WAIT_V(6); PG8_BAR; PG8_MMA(1, 1, At, B1); PG8_BAR;
;         }
;         epilogue(cur.kind, p, acc, cur, wr, wc, fr, fq);
	s_waitcnt lgkmcnt(0)
	s_waitcnt lgkmcnt(0)
	v_mfma_f32_16x16x32_bf16 v[60:63], v[132:135], v[148:151], v[60:63]
	v_mfma_f32_16x16x32_bf16 v[56:59], v[140:143], v[148:151], v[56:59]
	v_mfma_f32_16x16x32_bf16 v[52:55], v[132:135], v[156:159], v[52:55]
	v_mfma_f32_16x16x32_bf16 v[48:51], v[140:143], v[156:159], v[48:51]
	v_mfma_f32_16x16x32_bf16 v[44:47], v[132:135], v[176:179], v[44:47]
	v_mfma_f32_16x16x32_bf16 v[40:43], v[140:143], v[176:179], v[40:43]
	v_mfma_f32_16x16x32_bf16 v[36:39], v[132:135], v[184:187], v[36:39]
	v_mfma_f32_16x16x32_bf16 v[32:35], v[140:143], v[184:187], v[32:35]
	v_mfma_f32_16x16x32_bf16 v[60:63], v[136:139], v[152:155], v[60:63]
	v_mfma_f32_16x16x32_bf16 v[56:59], v[144:147], v[152:155], v[56:59]
	v_mfma_f32_16x16x32_bf16 v[52:55], v[136:139], v[172:175], v[52:55]
	v_mfma_f32_16x16x32_bf16 v[48:51], v[144:147], v[172:175], v[48:51]
	v_mfma_f32_16x16x32_bf16 v[44:47], v[136:139], v[180:183], v[44:47]
	v_mfma_f32_16x16x32_bf16 v[40:43], v[144:147], v[180:183], v[40:43]
	v_mfma_f32_16x16x32_bf16 v[36:39], v[136:139], v[188:191], v[36:39]
	v_mfma_f32_16x16x32_bf16 v[32:35], v[144:147], v[188:191], v[32:35]
	s_barrier
	s_add_i32 s12, s12, s64
	v_lshl_add_u64 v[132:133], v[240:241], 0, s[90:91]
	s_mov_b32 m0, s12
	s_nop 0
	global_load_lds_dwordx4 v[132:133], off
	v_lshl_add_u64 v[132:133], v[242:243], 0, s[90:91]
	s_add_i32 m0, s12, 0x2000
	s_nop 0
	global_load_lds_dwordx4 v[132:133], off
	s_waitcnt vmcnt(6)
	s_barrier
	v_mfma_f32_16x16x32_bf16 v[28:31], v[216:219], v[148:151], v[28:31]
	v_mfma_f32_16x16x32_bf16 v[24:27], v[224:227], v[148:151], v[24:27]
	v_mfma_f32_16x16x32_bf16 v[20:23], v[216:219], v[156:159], v[20:23]
	v_mfma_f32_16x16x32_bf16 v[16:19], v[224:227], v[156:159], v[16:19]
	v_mfma_f32_16x16x32_bf16 v[12:15], v[216:219], v[176:179], v[12:15]
	v_mfma_f32_16x16x32_bf16 v[8:11], v[224:227], v[176:179], v[8:11]
	v_mfma_f32_16x16x32_bf16 v[4:7], v[216:219], v[184:187], v[4:7]
	v_mfma_f32_16x16x32_bf16 v[0:3], v[224:227], v[184:187], v[0:3]
	v_mfma_f32_16x16x32_bf16 v[28:31], v[220:223], v[152:155], v[28:31]
	v_mfma_f32_16x16x32_bf16 v[24:27], v[228:231], v[152:155], v[24:27]
	v_mfma_f32_16x16x32_bf16 v[20:23], v[220:223], v[172:175], v[20:23]
	v_mfma_f32_16x16x32_bf16 v[16:19], v[228:231], v[172:175], v[16:19]
	v_mfma_f32_16x16x32_bf16 v[12:15], v[220:223], v[180:183], v[12:15]
	v_mfma_f32_16x16x32_bf16 v[8:11], v[228:231], v[180:183], v[8:11]
	v_mfma_f32_16x16x32_bf16 v[4:7], v[220:223], v[188:191], v[4:7]
	v_mfma_f32_16x16x32_bf16 v[0:3], v[228:231], v[188:191], v[0:3]
	s_add_u32 s10, s10, 0x100
	s_addc_u32 s11, s11, 0
	s_cmp_ge_u32 s1, s84
	s_barrier
	s_cbranch_scc0 .LBB0_631
	v_mov_b32_e32 v215, v211
	v_mov_b32_e32 v216, v212
	s_cmp_eq_u32 s3, 13
	s_cbranch_scc1 .Lmy_down
	s_cmp_eq_u32 s3, 12
	s_cbranch_scc1 .Lmy_ffn1
	s_cmp_lt_i32 s3, 7
	v_lshl_add_u32 v172, v216, 3, s31
	s_mov_b64 s[10:11], -1
	s_cbranch_scc1 .LBB0_849
	s_cmp_lt_i32 s3, 11
	s_cbranch_scc1 .LBB0_639
	s_cmp_gt_i32 s3, 12
	s_cbranch_scc0 .LBB0_640
	s_cmp_gt_i32 s3, 13
	s_mov_b64 s[26:27], -1
	s_cbranch_scc0 .LBB0_641
	s_cmp_eq_u32 s3, 14
	s_cbranch_scc0 .LBB0_638
	v_add_u32_e32 v128, s0, v215
	s_ashr_i32 s79, s78, 31
	v_ashrrev_i32_e32 v129, 31, v128
	v_lshl_add_u64 v[130:131], v[128:129], 0, s[78:79]
	s_lshl_b32 s10, s92, 8
	v_lshlrev_b64 v[130:131], 12, v[130:131]
	s_ashr_i32 s11, s10, 31
	v_ashrrev_i32_e32 v173, 31, v172
	v_lshl_add_u64 v[130:131], s[82:83], 0, v[130:131]
	s_lshl_b64 s[10:11], s[10:11], 2
	v_lshl_add_u64 v[130:131], v[130:131], 0, s[10:11]
	v_lshlrev_b64 v[132:133], 2, v[172:173]
	v_lshl_add_u64 v[130:131], v[130:131], 0, v[132:133]
	global_atomic_add_f32 v[130:131], v124, off
	global_atomic_add_f32 v[130:131], v120, off offset:16
	global_atomic_add_f32 v[130:131], v125, off offset:4
	global_atomic_add_f32 v[130:131], v121, off offset:20
	global_atomic_add_f32 v[130:131], v126, off offset:8
	global_atomic_add_f32 v[130:131], v122, off offset:24
	global_atomic_add_f32 v[130:131], v127, off offset:12
	global_atomic_add_f32 v[130:131], v123, off offset:28
	global_atomic_add_f32 v[130:131], v92, off offset:512
	global_atomic_add_f32 v[130:131], v88, off offset:528
	global_atomic_add_f32 v[130:131], v93, off offset:516
	global_atomic_add_f32 v[130:131], v89, off offset:532
	global_atomic_add_f32 v[130:131], v94, off offset:520
	global_atomic_add_f32 v[130:131], v90, off offset:536
	global_atomic_add_f32 v[130:131], v95, off offset:524
	global_atomic_add_f32 v[130:131], v91, off offset:540
	v_add_u32_e32 v130, 16, v128
	v_ashrrev_i32_e32 v131, 31, v130
	v_lshl_add_u64 v[130:131], v[130:131], 0, s[78:79]
	v_lshlrev_b64 v[130:131], 12, v[130:131]
	v_lshl_add_u64 v[130:131], s[82:83], 0, v[130:131]
	v_lshl_add_u64 v[130:131], v[130:131], 0, s[10:11]
	v_lshl_add_u64 v[130:131], v[130:131], 0, v[132:133]
	global_atomic_add_f32 v[130:131], v116, off
	global_atomic_add_f32 v[130:131], v112, off offset:16
	global_atomic_add_f32 v[130:131], v117, off offset:4
	global_atomic_add_f32 v[130:131], v113, off offset:20
	global_atomic_add_f32 v[130:131], v118, off offset:8
	global_atomic_add_f32 v[130:131], v114, off offset:24
	global_atomic_add_f32 v[130:131], v119, off offset:12
	global_atomic_add_f32 v[130:131], v115, off offset:28
	global_atomic_add_f32 v[130:131], v84, off offset:512
	global_atomic_add_f32 v[130:131], v80, off offset:528
	global_atomic_add_f32 v[130:131], v85, off offset:516
	global_atomic_add_f32 v[130:131], v81, off offset:532
	global_atomic_add_f32 v[130:131], v86, off offset:520
	global_atomic_add_f32 v[130:131], v82, off offset:536
	global_atomic_add_f32 v[130:131], v87, off offset:524
; #define FOR_ROWS _Pragma("unroll") for (int ai = 0; ai < 2; ++ai) _Pragma("unroll") for (int m = 0; m < 4; ++m)
; __device__ __forceinline__ void epilogue(const int kind, CParams& p, const f32x4 (&acc)[2][2][4][2], const Unit& u, const int wr, const int wc, const int fr_in, const int fq_in) {
;     ...
;     case E_DOWN_HALF: {
;         FOR_ROWS { ROWDEF
; #pragma unroll
;             for (int bj = 0; bj < 2; ++bj) { float* hp = p.out + row * 1024 + u.pn * 256 + bj * 128 + cw;
; #pragma unroll
;                 for (int j = 0; j < 4; ++j) { unsafeAtomicAdd(hp + j, acc[ai][bj][m][0][j]); unsafeAtomicAdd(hp + 4 + j, acc[ai][bj][m][1][j]); } } }
;     } break;
	global_atomic_add_f32 v[130:131], v83, off offset:540
	v_add_u32_e32 v130, 32, v128
	v_ashrrev_i32_e32 v131, 31, v130
	v_lshl_add_u64 v[130:131], v[130:131], 0, s[78:79]
	v_lshlrev_b64 v[130:131], 12, v[130:131]
	v_lshl_add_u64 v[130:131], s[82:83], 0, v[130:131]
	v_lshl_add_u64 v[130:131], v[130:131], 0, s[10:11]
	v_lshl_add_u64 v[130:131], v[130:131], 0, v[132:133]
	global_atomic_add_f32 v[130:131], v108, off
	global_atomic_add_f32 v[130:131], v104, off offset:16
	global_atomic_add_f32 v[130:131], v109, off offset:4
	global_atomic_add_f32 v[130:131], v105, off offset:20
	global_atomic_add_f32 v[130:131], v110, off offset:8
	global_atomic_add_f32 v[130:131], v106, off offset:24
	global_atomic_add_f32 v[130:131], v111, off offset:12
	global_atomic_add_f32 v[130:131], v107, off offset:28
	global_atomic_add_f32 v[130:131], v76, off offset:512
	global_atomic_add_f32 v[130:131], v72, off offset:528
	global_atomic_add_f32 v[130:131], v77, off offset:516
	global_atomic_add_f32 v[130:131], v73, off offset:532
	global_atomic_add_f32 v[130:131], v78, off offset:520
	global_atomic_add_f32 v[130:131], v74, off offset:536
	global_atomic_add_f32 v[130:131], v79, off offset:524
	global_atomic_add_f32 v[130:131], v75, off offset:540
	v_add_u32_e32 v130, 48, v128
	v_ashrrev_i32_e32 v131, 31, v130
	v_lshl_add_u64 v[130:131], v[130:131], 0, s[78:79]
	v_lshlrev_b64 v[130:131], 12, v[130:131]
	v_lshl_add_u64 v[130:131], s[82:83], 0, v[130:131]
	v_lshl_add_u64 v[130:131], v[130:131], 0, s[10:11]
	v_lshl_add_u64 v[130:131], v[130:131], 0, v[132:133]
	global_atomic_add_f32 v[130:131], v100, off
	global_atomic_add_f32 v[130:131], v96, off offset:16
	global_atomic_add_f32 v[130:131], v101, off offset:4
	global_atomic_add_f32 v[130:131], v97, off offset:20
	global_atomic_add_f32 v[130:131], v102, off offset:8
	global_atomic_add_f32 v[130:131], v98, off offset:24
	global_atomic_add_f32 v[130:131], v103, off offset:12
	global_atomic_add_f32 v[130:131], v99, off offset:28
	global_atomic_add_f32 v[130:131], v68, off offset:512
	global_atomic_add_f32 v[130:131], v64, off offset:528
	global_atomic_add_f32 v[130:131], v69, off offset:516
	global_atomic_add_f32 v[130:131], v65, off offset:532
	global_atomic_add_f32 v[130:131], v70, off offset:520
	global_atomic_add_f32 v[130:131], v66, off offset:536
	global_atomic_add_f32 v[130:131], v71, off offset:524
	global_atomic_add_f32 v[130:131], v67, off offset:540
	v_add_u32_e32 v130, 0x80, v128
	v_ashrrev_i32_e32 v131, 31, v130
	v_lshl_add_u64 v[130:131], v[130:131], 0, s[78:79]
	v_lshlrev_b64 v[130:131], 12, v[130:131]
	v_lshl_add_u64 v[130:131], s[82:83], 0, v[130:131]
	v_lshl_add_u64 v[130:131], v[130:131], 0, s[10:11]
	v_lshl_add_u64 v[130:131], v[130:131], 0, v[132:133]
	global_atomic_add_f32 v[130:131], v60, off
	global_atomic_add_f32 v[130:131], v56, off offset:16
	global_atomic_add_f32 v[130:131], v61, off offset:4
	global_atomic_add_f32 v[130:131], v57, off offset:20
	global_atomic_add_f32 v[130:131], v62, off offset:8
	global_atomic_add_f32 v[130:131], v58, off offset:24
	global_atomic_add_f32 v[130:131], v63, off offset:12
	global_atomic_add_f32 v[130:131], v59, off offset:28
	global_atomic_add_f32 v[130:131], v28, off offset:512
	global_atomic_add_f32 v[130:131], v24, off offset:528
	global_atomic_add_f32 v[130:131], v29, off offset:516
	global_atomic_add_f32 v[130:131], v25, off offset:532
	global_atomic_add_f32 v[130:131], v30, off offset:520
	global_atomic_add_f32 v[130:131], v26, off offset:536
	global_atomic_add_f32 v[130:131], v31, off offset:524
; #define FOR_ROWS _Pragma("unroll") for (int ai = 0; ai < 2; ++ai) _Pragma("unroll") for (int m = 0; m < 4; ++m)
; __device__ __forceinline__ void epilogue(const int kind, CParams& p, const f32x4 (&acc)[2][2][4][2], const Unit& u, const int wr, const int wc, const int fr_in, const int fq_in) {
;     ...
;     case E_DOWN_HALF: {
;         FOR_ROWS { ROWDEF
; #pragma unroll
;             for (int bj = 0; bj < 2; ++bj) { float* hp = p.out + row * 1024 + u.pn * 256 + bj * 128 + cw;
; #pragma unroll
;                 for (int j = 0; j < 4; ++j) { unsafeAtomicAdd(hp + j, acc[ai][bj][m][0][j]); unsafeAtomicAdd(hp + 4 + j, acc[ai][bj][m][1][j]); } } }
;     } break;
	global_atomic_add_f32 v[130:131], v27, off offset:540
	v_add_u32_e32 v130, 0x90, v128
	v_ashrrev_i32_e32 v131, 31, v130
	v_lshl_add_u64 v[130:131], v[130:131], 0, s[78:79]
	v_lshlrev_b64 v[130:131], 12, v[130:131]
	v_lshl_add_u64 v[130:131], s[82:83], 0, v[130:131]
	v_lshl_add_u64 v[130:131], v[130:131], 0, s[10:11]
	v_lshl_add_u64 v[130:131], v[130:131], 0, v[132:133]
	global_atomic_add_f32 v[130:131], v52, off
	global_atomic_add_f32 v[130:131], v48, off offset:16
	global_atomic_add_f32 v[130:131], v53, off offset:4
	global_atomic_add_f32 v[130:131], v49, off offset:20
	global_atomic_add_f32 v[130:131], v54, off offset:8
	global_atomic_add_f32 v[130:131], v50, off offset:24
	global_atomic_add_f32 v[130:131], v55, off offset:12
	global_atomic_add_f32 v[130:131], v51, off offset:28
	global_atomic_add_f32 v[130:131], v20, off offset:512
	global_atomic_add_f32 v[130:131], v16, off offset:528
	global_atomic_add_f32 v[130:131], v21, off offset:516
	global_atomic_add_f32 v[130:131], v17, off offset:532
	global_atomic_add_f32 v[130:131], v22, off offset:520
	global_atomic_add_f32 v[130:131], v18, off offset:536
	global_atomic_add_f32 v[130:131], v23, off offset:524
	global_atomic_add_f32 v[130:131], v19, off offset:540
	v_add_u32_e32 v130, 0xa0, v128
	v_ashrrev_i32_e32 v131, 31, v130
	v_add_u32_e32 v128, 0xb0, v128
	v_lshl_add_u64 v[130:131], v[130:131], 0, s[78:79]
	v_ashrrev_i32_e32 v129, 31, v128
	v_lshlrev_b64 v[130:131], 12, v[130:131]
	v_lshl_add_u64 v[128:129], v[128:129], 0, s[78:79]
	v_lshl_add_u64 v[130:131], s[82:83], 0, v[130:131]
	v_lshlrev_b64 v[128:129], 12, v[128:129]
	v_lshl_add_u64 v[130:131], v[130:131], 0, s[10:11]
	v_lshl_add_u64 v[128:129], s[82:83], 0, v[128:129]
	v_lshl_add_u64 v[130:131], v[130:131], 0, v[132:133]
	v_lshl_add_u64 v[128:129], v[128:129], 0, s[10:11]
	global_atomic_add_f32 v[130:131], v44, off
	global_atomic_add_f32 v[130:131], v40, off offset:16
	global_atomic_add_f32 v[130:131], v45, off offset:4
	global_atomic_add_f32 v[130:131], v41, off offset:20
	global_atomic_add_f32 v[130:131], v46, off offset:8
	global_atomic_add_f32 v[130:131], v42, off offset:24
	global_atomic_add_f32 v[130:131], v47, off offset:12
	global_atomic_add_f32 v[130:131], v43, off offset:28
	global_atomic_add_f32 v[130:131], v12, off offset:512
	global_atomic_add_f32 v[130:131], v8, off offset:528
	global_atomic_add_f32 v[130:131], v13, off offset:516
	global_atomic_add_f32 v[130:131], v9, off offset:532
	global_atomic_add_f32 v[130:131], v14, off offset:520
	global_atomic_add_f32 v[130:131], v10, off offset:536
	global_atomic_add_f32 v[130:131], v15, off offset:524
	global_atomic_add_f32 v[130:131], v11, off offset:540
	v_lshl_add_u64 v[128:129], v[128:129], 0, v[132:133]
	global_atomic_add_f32 v[128:129], v36, off
	global_atomic_add_f32 v[128:129], v32, off offset:16
	global_atomic_add_f32 v[128:129], v37, off offset:4
	global_atomic_add_f32 v[128:129], v33, off offset:20
	global_atomic_add_f32 v[128:129], v38, off offset:8
	global_atomic_add_f32 v[128:129], v34, off offset:24
	global_atomic_add_f32 v[128:129], v39, off offset:12
	global_atomic_add_f32 v[128:129], v35, off offset:28
	global_atomic_add_f32 v[128:129], v4, off offset:512
	global_atomic_add_f32 v[128:129], v0, off offset:528
	global_atomic_add_f32 v[128:129], v5, off offset:516
	global_atomic_add_f32 v[128:129], v1, off offset:532
	global_atomic_add_f32 v[128:129], v6, off offset:520
	global_atomic_add_f32 v[128:129], v2, off offset:536
	global_atomic_add_f32 v[128:129], v7, off offset:524
	global_atomic_add_f32 v[128:129], v3, off offset:540
